# attention loop: static s_setprio 1 for waves 4-7 on top of VALU row sums
# baseline (speedup 1.0000x reference)
; DI void attn_item(const Params& p, int layer, int item, char* smem) {
;   const int tid = tidx(), lane = tid & 63, wid = tid >> 6, l32 = lane & 31, h = lane >> 5;
;   int mode, b, hh, qb;
;   if (item < NAT_C) { mode = 0; b = item / 96; int rem = item % 96; hh = rem >> 4; qb = rem & 15; }
;   else if (item < NAT_C + NAT_B) { int it = item - NAT_C; mode = 1; b = it >> 6; hh = (it & 63) >> 4; qb = it & 15; }
;   else if (item < NAT_LAT) { int it = item - NAT_C - NAT_B; mode = 2; b = it / 96; int rem = it % 96; hh = rem >> 4; qb = rem & 15; }
;   else { int it = item - NAT_LAT; mode = 3; b = it >> 4; hh = it & 15; qb = 0; }
;   int qchunk, kchunk, vchunk, head16, t0 = 0, t1 = 0, qpos0 = qb * 256;
;   bool hasSink = false; float sinkv = 0.f;
;   int maskmode = 0;
;   if (mode == 0) { qchunk = 22 + hh; kchunk = 28 + hh / 3; vchunk = 30 + hh / 3; head16 = 10 + hh; t0 = 0; t1 = 64; }
;   else if (mode == 1) {
;     qchunk = 10 + hh; kchunk = 14 + hh; vchunk = 18 + hh; head16 = 6 + hh; maskmode = 1;
;     t0 = min(max(4 * qb - 4, 0), 56); t1 = min(max(4 * qb + 3 - 4, 0), 56) + 8;
;   } else if (mode == 2) {
;     qchunk = hh; kchunk = 6 + hh / 3; vchunk = 8 + hh / 3; head16 = hh; maskmode = 2;
;     t0 = max(0, 4 * qb - 2); t1 = min(64, 4 * qb + 6); hasSink = true; sinkv = p.sink[layer * 6 + hh];
;   } else {
;     head16 = hh; qpos0 = 4096;
;     if (hh < 6) { qchunk = hh; kchunk = 6 + hh / 3; vchunk = 8 + hh / 3; hasSink = true; sinkv = p.sink[layer * 6 + hh]; }
;     else if (hh < 10) { int hb = hh - 6; qchunk = 10 + hb; kchunk = 14 + hb; vchunk = 18 + hb; }
;     else { int hc = hh - 10; qchunk = 22 + hc; kchunk = 28 + hc / 3; vchunk = 30 + hc / 3; }
;   }
;   const int n_it = 4 + (t1 - t0);
;   const u16* Qb = p.QKV + (size_t)(b * 32 + qchunk) * LTOT * 64;
;   const u16* Kb = p.QKV + (size_t)(b * 32 + kchunk) * LTOT * 64;
;   const u16* Vb = p.QKV + (size_t)(b * 32 + vchunk) * LTOT * 64;
;   float* s_rpb = (float*)(smem + RPB_OFF);
;   if (mode == 1) {
;     const float* rp = p.rpb + (size_t)(layer * 4 + hh) * 465;
;     for (int e = tid; e < 465; e += NTHR) s_rpb[e] = rp[e] * LOG2E;
;   }
;   const int qpos = qpos0 + wid * 32 + l32;
;   bf16x8 qf[4];
; #pragma unroll
;   for (int s = 0; s < 4; ++s) qf[s] = *(const bf16x8*)(Qb + (size_t)qpos * 64 + s * 16 + h * 8);
;   f32x16 o0, o1;
; #pragma unroll
.LBB0_259:
	s_mul_hi_i32 s0, s14, 0x2aaaaaab
	s_lshr_b32 s1, s0, 31
	s_ashr_i32 s5, s0, 4
	s_add_i32 s5, s5, s1
	s_mul_i32 s0, s5, 0x60
	s_sub_i32 s0, s14, s0
	v_mov_b32_e32 v32, v213
	s_ashr_i32 s4, s0, 4
	s_lshl_b32 s0, s0, 8
	s_and_b32 s8, s0, 0xf00
	s_lshl_b32 s0, s5, 5
	v_ashrrev_i32_e32 v0, 1, v32
	s_add_i32 s1, s4, s0
	s_mul_i32 s2, s4, 0x56
	v_and_b32_e32 v0, 0xffffffe0, v0
	v_and_b32_e32 v36, 31, v32
	s_bfe_u32 s3, s2, 0x1000f
	s_bfe_u32 s2, s2, 0x80008
	s_add_i32 s1, s1, 22
	v_add_u32_e32 v0, s8, v0
	s_add_i32 s2, s2, s3
	s_mul_hi_i32 s3, s1, 0x88000
	s_mul_i32 s1, s1, 0x88000
	v_or_b32_e32 v134, v0, v36
	s_add_u32 s6, s88, s1
	v_ashrrev_i32_e32 v135, 31, v134
	v_bfe_u32 v140, v32, 5, 1
	s_addc_u32 s7, s89, s3
	v_lshlrev_b64 v[2:3], 7, v[134:135]
	v_lshl_add_u64 v[2:3], s[6:7], 0, v[2:3]
	v_lshlrev_b32_e32 v18, 4, v140
	v_mov_b32_e32 v19, v1
	v_readlane_b32 s6, v254, 50
	v_lshl_add_u64 v[2:3], v[2:3], 0, v[18:19]
	v_readlane_b32 s7, v254, 51
	global_load_dwordx4 v[98:101], v[2:3], off
	global_load_dwordx4 v[102:105], v[2:3], off offset:32
	global_load_dwordx4 v[106:109], v[2:3], off offset:64
	global_load_dwordx4 v[110:113], v[2:3], off offset:96
	s_sext_i32_i8 s2, s2
	global_load_dword v0, v1, s[6:7] offset:8
	s_add_i32 s2, s0, s2
	s_mul_i32 s3, s2, 0x88000
	s_add_i32 s0, s2, 28
	s_mul_hi_i32 s1, s0, 0x88000
	s_add_i32 s0, s3, 0xee0000
	v_ashrrev_i32_e32 v30, 3, v32
	s_add_u32 s0, s88, s0
	v_ashrrev_i32_e32 v31, 31, v30
	s_addc_u32 s1, s89, s1
	v_lshlrev_b32_e32 v19, 4, v32
	v_lshlrev_b64 v[20:21], 7, v[30:31]
	v_lshl_add_u64 v[136:137], s[0:1], 0, v[20:21]
	s_mov_b32 s6, 0x80000
	s_add_i32 s2, s2, 30
	s_add_i32 s3, s3, 0xff0000
	s_mul_hi_i32 s9, s2, 0x88000
	s_add_u32 s2, s88, s3
	s_addc_u32 s3, s89, s9
	v_mov_b64_e32 v[26:27], s[2:3]
	v_mad_i64_i32 v[138:139], s[2:3], v30, s28, v[26:27]
	s_movk_i32 s3, 0x90
	s_mov_b32 s2, 0x82000
	v_mul_lo_u32 v30, v30, s3
	v_add_u32_e32 v30, 16, v30
	v_add_u32_e32 v144, 16, v18
	v_mul_u32_u24_e32 v145, 0x90, v36
	v_mad_u32_u24 v146, v36, s3, v144
	s_waitcnt vmcnt(0)
	v_xor_b32_e32 v2, 0x80000000, v0
	v_and_b32_e32 v0, 0x70, v19
	v_lshl_add_u64 v[34:35], v[136:137], 0, v[0:1]
	v_add_co_u32_e32 v22, vcc, s6, v34
	v_add_u32_e32 v135, v30, v0
	s_nop 0
	v_addc_co_u32_e32 v23, vcc, 0, v35, vcc
	global_load_dwordx4 v[22:25], v[22:23], off
	v_add_co_u32_e32 v26, vcc, s2, v34
	v_lshl_add_u64 v[74:75], v[138:139], 0, v[0:1]
	s_nop 0
	v_addc_co_u32_e32 v27, vcc, 0, v35, vcc
	global_load_dwordx4 v[26:29], v[26:27], off
	s_movk_i32 s2, 0x2000
	v_mov_b32_e32 v3, v2
	v_mov_b32_e32 v4, v2
	v_mov_b32_e32 v5, v2
	v_mov_b32_e32 v6, v2
	v_mov_b32_e32 v7, v2
	v_mov_b32_e32 v8, v2
	v_mov_b32_e32 v9, v2
	v_mov_b32_e32 v10, v2
	v_mov_b32_e32 v11, v2
	v_mov_b32_e32 v12, v2
	v_mov_b32_e32 v13, v2
	v_mov_b32_e32 v14, v2
	v_mov_b32_e32 v15, v2
	v_mov_b32_e32 v16, v2
	v_mov_b32_e32 v17, v2
	s_waitcnt vmcnt(0)
	ds_write_b128 v135, v[22:25]
	v_lshlrev_b32_e32 v22, 3, v32
	v_and_b32_e32 v22, 8, v22
	v_and_or_b32 v19, v19, s74, v22
	v_add_co_u32_e32 v22, vcc, s2, v74
	v_add_u32_e32 v19, v30, v19
	s_nop 0
	v_addc_co_u32_e32 v23, vcc, 0, v75, vcc
	global_load_dwordx4 v[30:33], v[22:23], off
	s_mov_b32 s2, 0x84000
	v_add_co_u32_e32 v24, vcc, s2, v34
	v_add_u32_e32 v141, 0x2000, v19
	s_nop 0
	v_addc_co_u32_e32 v25, vcc, 0, v35, vcc
	global_load_dwordx4 v[66:69], v[24:25], off
	v_lshl_add_u64 v[24:25], s[0:1], 0, v[0:1]
	v_lshl_add_u64 v[76:77], v[24:25], 0, v[20:21]
	s_mov_b32 s0, 0x86000
	v_add_u32_e32 v143, 0x6800, v19
	s_waitcnt vmcnt(0)
	ds_write2_b64 v141, v[30:31], v[32:33] offset0:128 offset1:130
	v_mad_u32_u24 v30, v36, s3, 16
	v_add_u32_e32 v142, v30, v18
	global_load_dwordx4 v[70:73], v[22:23], off offset:256
	global_load_dwordx4 v[30:33], v[22:23], off offset:128
	v_add_co_u32_e32 v18, vcc, s0, v76
	s_waitcnt lgkmcnt(0)
	s_barrier
	ds_write_b128 v135, v[26:29] offset:18432
	v_addc_co_u32_e32 v19, vcc, 0, v77, vcc
	s_waitcnt vmcnt(0)
	ds_write2_b64 v143, v[30:31], v[32:33] offset0:128 offset1:130
	global_load_dwordx4 v[114:117], v[18:19], off
	global_load_dwordx4 v[118:121], v[22:23], off offset:384
	ds_read_b128 v[34:37], v146
	ds_read_b128 v[38:41], v146 offset:32
	v_mov_b64_e32 v[132:133], s[94:95]
	v_mov_b64_e32 v[130:131], s[92:93]
	s_waitcnt lgkmcnt(1)
	v_mfma_f32_32x32x16_bf16 v[18:33], v[34:37], v[98:101], v[2:17]
	ds_read_b128 v[34:37], v146 offset:64
	ds_read_b128 v[50:53], v146 offset:4608
	s_waitcnt lgkmcnt(2)
	v_mfma_f32_32x32x16_bf16 v[18:33], v[38:41], v[102:105], v[18:33]
	s_waitcnt lgkmcnt(1)
	v_mfma_f32_32x32x16_bf16 v[18:33], v[34:37], v[106:109], v[18:33]
	ds_read_b128 v[34:37], v146 offset:96
	s_waitcnt lgkmcnt(0)
	v_mfma_f32_32x32x16_bf16 v[18:33], v[34:37], v[110:113], v[18:33]
	v_mfma_f32_32x32x16_bf16 v[34:49], v[50:53], v[98:101], v[2:17]
	ds_read_b128 v[50:53], v146 offset:4640
	s_nop 9
	v_exp_f32_e32 v18, v18
	v_exp_f32_e32 v19, v19
	v_exp_f32_e32 v20, v20
	v_exp_f32_e32 v21, v21
	v_exp_f32_e32 v22, v22
	v_exp_f32_e32 v23, v23
	s_waitcnt lgkmcnt(0)
	v_mfma_f32_32x32x16_bf16 v[34:49], v[50:53], v[102:105], v[34:49]
	ds_read_b128 v[50:53], v146 offset:4672
	v_exp_f32_e32 v24, v24
	v_exp_f32_e32 v25, v25
	v_cvt_pk_bf16_f32 v18, v18, v19
	v_cvt_pk_bf16_f32 v19, v20, v21
	v_cvt_pk_bf16_f32 v20, v22, v23
	v_cvt_pk_bf16_f32 v21, v24, v25
	s_waitcnt lgkmcnt(0)
	v_mfma_f32_32x32x16_bf16 v[34:49], v[50:53], v[106:109], v[34:49]
	ds_read_b128 v[50:53], v146 offset:4704
	ds_read_b128 v[22:25], v142 offset:9216
	ds_read_b128 v[78:81], v142 offset:9248
	v_exp_f32_e32 v82, v26
	v_exp_f32_e32 v83, v27
	v_exp_f32_e32 v84, v28
	v_exp_f32_e32 v85, v29
	v_exp_f32_e32 v122, v30
	s_waitcnt lgkmcnt(2)
; #define MFMA32(a, b, c) __builtin_amdgcn_mfma_f32_32x32x16_bf16((a), (b), (c), 0, 0, 0)
; DI void attn_item(const Params& p, int layer, int item, char* smem) {
;     ...
; #pragma unroll
;       for (int r = 0; r < 16; ++r) {
;         S[0][r] = __builtin_amdgcn_exp2f(S[0][r]);
;         S[1][r] = __builtin_amdgcn_exp2f(S[1][r]);
;       }
; #pragma unroll
;       for (int kt = 0; kt < 2; ++kt)
; #pragma unroll
;         for (int s2 = 0; s2 < 2; ++s2) {
;           uint4 pw;
;           pw.x = pack_bf16(S[kt][8 * s2 + 0], S[kt][8 * s2 + 1]);
;           pw.y = pack_bf16(S[kt][8 * s2 + 2], S[kt][8 * s2 + 3]);
;           pw.z = pack_bf16(S[kt][8 * s2 + 4], S[kt][8 * s2 + 5]);
;           pw.w = pack_bf16(S[kt][8 * s2 + 6], S[kt][8 * s2 + 7]);
;           bf16x8 pf = __builtin_bit_cast(bf16x8, pw);
;           const int koff = (kt * 32 + 16 * s2 + 8 * h) * 2;
;           {
;             bf16x8 vf = *(const bf16x8*)(sV + l32 * VROW + koff);
;             o0 = MFMA32(vf, pf, o0);
;             lacc = MFMA32(ones, pf, lacc);
;           }
;           {
;             bf16x8 vf = *(const bf16x8*)(sV + (32 + l32) * VROW + koff);
;             o1 = MFMA32(vf, pf, o1);
;           }
;         }
;     ...
;   for (int it = 0; it < n_it; it += 2) {
;     if (it + 1 < n_it) { ASWRITE(kb0, vb0, 1); }
;     if (it + 3 < n_it) { AGLOAD(kb0, vb0, TILE_OF(it + 3)); }
;     __builtin_amdgcn_sched_barrier(0);
;     compute(0, TILE_OF(it));
;     __syncthreads();
;     if (it + 1 < n_it) {
;       if (it + 2 < n_it) { ASWRITE(ka0, va0, 0); }
;       if (it + 4 < n_it) { AGLOAD(ka0, va0, TILE_OF(it + 4)); }
;       __builtin_amdgcn_sched_barrier(0);
;       compute(1, TILE_OF(it + 1));
;       __syncthreads();
	v_mfma_f32_32x32x16_bf16 v[34:49], v[50:53], v[110:113], v[34:49]
	v_exp_f32_e32 v124, v31
	v_exp_f32_e32 v126, v32
	v_exp_f32_e32 v128, v33
	v_cvt_pk_bf16_f32 v82, v82, v83
	v_cvt_pk_bf16_f32 v83, v84, v85
	v_cvt_pk_bf16_f32 v84, v122, v124
	v_cvt_pk_bf16_f32 v85, v126, v128
	s_nop 4
	v_exp_f32_e32 v86, v34
	v_exp_f32_e32 v87, v35
	v_exp_f32_e32 v88, v36
	v_exp_f32_e32 v89, v37
	v_exp_f32_e32 v90, v38
	v_exp_f32_e32 v91, v39
	v_exp_f32_e32 v92, v40
	v_exp_f32_e32 v93, v41
	v_exp_f32_e32 v94, v42
	v_exp_f32_e32 v95, v43
	v_exp_f32_e32 v96, v44
	v_exp_f32_e32 v97, v45
	v_exp_f32_e32 v123, v46
	v_exp_f32_e32 v125, v47
	v_exp_f32_e32 v127, v48
	v_exp_f32_e32 v129, v49
	s_waitcnt lgkmcnt(1)
	v_mfma_f32_32x32x16_bf16 v[34:49], v[22:25], v[18:21], 0
	ds_read_b128 v[22:25], v142 offset:13824
	s_waitcnt lgkmcnt(1)
	v_mfma_f32_32x32x16_bf16 v[34:49], v[78:81], v[82:85], v[34:49]
	ds_read_b128 v[78:81], v142 offset:13856
	v_mfma_f32_32x32x16_bf16 v[50:65], v[130:133], v[18:21], 0
	s_waitcnt lgkmcnt(1)
	v_mfma_f32_32x32x16_bf16 v[18:33], v[22:25], v[18:21], 0
	v_mfma_f32_32x32x16_bf16 v[50:65], v[130:133], v[82:85], v[50:65]
	s_waitcnt lgkmcnt(0)
	v_mfma_f32_32x32x16_bf16 v[18:33], v[78:81], v[82:85], v[18:33]
	ds_read_b128 v[82:85], v142 offset:9280
	v_cvt_pk_bf16_f32 v78, v86, v87
	v_cvt_pk_bf16_f32 v79, v88, v89
	v_cvt_pk_bf16_f32 v80, v90, v91
	v_cvt_pk_bf16_f32 v81, v92, v93
	s_waitcnt lgkmcnt(0)
	s_nop 0
	v_mfma_f32_32x32x16_bf16 v[34:49], v[82:85], v[78:81], v[34:49]
	ds_read_b128 v[82:85], v142 offset:13888
	s_waitcnt lgkmcnt(0)
	v_mfma_f32_32x32x16_bf16 v[18:33], v[82:85], v[78:81], v[18:33]
	ds_read_b128 v[82:85], v142 offset:9312
	v_mfma_f32_32x32x16_bf16 v[50:65], v[130:133], v[78:81], v[50:65]
	v_cvt_pk_bf16_f32 v78, v94, v95
	v_cvt_pk_bf16_f32 v79, v96, v97
	v_cvt_pk_bf16_f32 v80, v123, v125
	v_cvt_pk_bf16_f32 v81, v127, v129
	s_waitcnt lgkmcnt(0)
	s_nop 0
	v_mfma_f32_32x32x16_bf16 v[34:49], v[82:85], v[78:81], v[34:49]
	ds_read_b128 v[82:85], v142 offset:13920
	s_waitcnt lgkmcnt(0)
	s_barrier
	ds_write_b128 v135, v[66:69]
	ds_write2_b64 v141, v[70:71], v[72:73] offset0:128 offset1:130
	global_load_dwordx4 v[122:125], v[76:77], off
	global_load_dwordx4 v[126:129], v[74:75], off
	v_mfma_f32_32x32x16_bf16 v[50:65], v[130:133], v[78:81], v[50:65]
	v_mfma_f32_32x32x16_bf16 v[18:33], v[82:85], v[78:81], v[18:33]
	ds_read_b128 v[82:85], v146 offset:18432
	ds_read_b128 v[86:89], v146 offset:18464
	s_mov_b32 s2, 2
	v_add_u32_e32 v144, v144, v145
	s_waitcnt lgkmcnt(1)
	v_mfma_f32_32x32x16_bf16 v[66:81], v[82:85], v[98:101], v[2:17]
	ds_read_b128 v[82:85], v146 offset:18496
	ds_read_b128 v[148:151], v146 offset:23040
	s_waitcnt lgkmcnt(2)
	v_mfma_f32_32x32x16_bf16 v[66:81], v[86:89], v[102:105], v[66:81]
	s_waitcnt lgkmcnt(1)
	v_mfma_f32_32x32x16_bf16 v[66:81], v[82:85], v[106:109], v[66:81]
	ds_read_b128 v[82:85], v146 offset:18528
	s_waitcnt lgkmcnt(0)
	v_mfma_f32_32x32x16_bf16 v[66:81], v[82:85], v[110:113], v[66:81]
	v_mfma_f32_32x32x16_bf16 v[82:97], v[148:151], v[98:101], v[2:17]
	ds_read_b128 v[148:151], v146 offset:23072
	s_nop 9
	v_exp_f32_e32 v66, v66
	v_exp_f32_e32 v67, v67
	v_exp_f32_e32 v68, v68
	v_exp_f32_e32 v69, v69
	v_exp_f32_e32 v70, v70
	v_exp_f32_e32 v71, v71
	s_waitcnt lgkmcnt(0)
	v_mfma_f32_32x32x16_bf16 v[82:97], v[148:151], v[102:105], v[82:97]
	ds_read_b128 v[148:151], v146 offset:23104
	v_exp_f32_e32 v72, v72
	v_exp_f32_e32 v73, v73
	v_cvt_pk_bf16_f32 v66, v66, v67
	v_cvt_pk_bf16_f32 v67, v68, v69
	v_cvt_pk_bf16_f32 v68, v70, v71
	v_cvt_pk_bf16_f32 v69, v72, v73
	s_waitcnt lgkmcnt(0)
	v_mfma_f32_32x32x16_bf16 v[82:97], v[148:151], v[106:109], v[82:97]
	ds_read_b128 v[146:149], v146 offset:23136
	v_exp_f32_e32 v78, v78
	v_exp_f32_e32 v79, v79
	v_exp_f32_e32 v80, v80
	v_exp_f32_e32 v81, v81
	s_waitcnt lgkmcnt(0)
	v_mfma_f32_32x32x16_bf16 v[82:97], v[146:149], v[110:113], v[82:97]
	v_exp_f32_e32 v146, v74
	v_exp_f32_e32 v147, v75
	v_exp_f32_e32 v148, v76
	v_exp_f32_e32 v149, v77
	ds_read_b128 v[70:73], v142 offset:27648
	ds_read_b128 v[74:77], v142 offset:27680
	s_nop 5
	v_exp_f32_e32 v82, v82
	s_waitcnt lgkmcnt(1)
	v_mfma_f32_32x32x16_bf16 v[34:49], v[70:73], v[66:69], v[34:49]
	ds_read_b128 v[70:73], v142 offset:32256
	v_exp_f32_e32 v83, v83
	v_exp_f32_e32 v84, v84
	v_exp_f32_e32 v85, v85
	v_exp_f32_e32 v86, v86
	v_exp_f32_e32 v87, v87
	v_exp_f32_e32 v88, v88
	s_waitcnt lgkmcnt(0)
	v_mfma_f32_32x32x16_bf16 v[18:33], v[70:73], v[66:69], v[18:33]
	ds_read_b128 v[70:73], v142 offset:32288
	v_exp_f32_e32 v89, v89
	v_exp_f32_e32 v90, v90
	v_exp_f32_e32 v91, v91
	v_exp_f32_e32 v92, v92
	v_exp_f32_e32 v93, v93
	v_exp_f32_e32 v94, v94
	v_mfma_f32_32x32x16_bf16 v[50:65], v[130:133], v[66:69], v[50:65]
	v_cvt_pk_bf16_f32 v66, v146, v147
	v_cvt_pk_bf16_f32 v67, v148, v149
	v_cvt_pk_bf16_f32 v68, v78, v79
	v_cvt_pk_bf16_f32 v69, v80, v81
	v_exp_f32_e32 v95, v95
	v_exp_f32_e32 v96, v96
	v_exp_f32_e32 v97, v97
	s_waitcnt lgkmcnt(0)
	v_mfma_f32_32x32x16_bf16 v[18:33], v[70:73], v[66:69], v[18:33]
	ds_read_b128 v[70:73], v142 offset:27712
	v_mfma_f32_32x32x16_bf16 v[34:49], v[74:77], v[66:69], v[34:49]
	v_mfma_f32_32x32x16_bf16 v[50:65], v[130:133], v[66:69], v[50:65]
	v_cvt_pk_bf16_f32 v66, v82, v83
	v_cvt_pk_bf16_f32 v67, v84, v85
	v_cvt_pk_bf16_f32 v68, v86, v87
	v_cvt_pk_bf16_f32 v69, v88, v89
	s_waitcnt lgkmcnt(0)
	s_nop 0
	v_mfma_f32_32x32x16_bf16 v[34:49], v[70:73], v[66:69], v[34:49]
	ds_read_b128 v[70:73], v142 offset:32320
	s_waitcnt lgkmcnt(0)
	v_mfma_f32_32x32x16_bf16 v[18:33], v[70:73], v[66:69], v[18:33]
	ds_read_b128 v[70:73], v142 offset:27744
	v_mfma_f32_32x32x16_bf16 v[50:65], v[130:133], v[66:69], v[50:65]
	v_cvt_pk_bf16_f32 v66, v90, v91
	v_cvt_pk_bf16_f32 v67, v92, v93
	v_cvt_pk_bf16_f32 v68, v94, v95
	v_cvt_pk_bf16_f32 v69, v96, v97
	s_waitcnt lgkmcnt(0)
	s_nop 0
	v_mfma_f32_32x32x16_bf16 v[34:49], v[70:73], v[66:69], v[34:49]
	ds_read_b128 v[70:73], v142 offset:32352
	s_waitcnt lgkmcnt(0)
	s_barrier
	v_mfma_f32_32x32x16_bf16 v[50:65], v[130:133], v[66:69], v[50:65]
	v_mfma_f32_32x32x16_bf16 v[18:33], v[70:73], v[66:69], v[18:33]
	s_nop 11
	v_mov_b32_e32 v51, 0
	v_mov_b32_e32 v52, 0
	v_readfirstlane_b32 s6, v213
	s_nop 3
	s_lshr_b32 s6, s6, 8
	s_cmp_eq_u32 s6, 1
	s_cbranch_scc0 .Lattn0_noprio
	s_setprio 1
; DI void attn_item(const Params& p, int layer, int item, char* smem) {
;     ...
;       f32x16 S[2];
; #pragma unroll
;       for (int kt = 0; kt < 2; ++kt) {
; #pragma unroll
;         for (int s = 0; s < 4; ++s) {
;           bf16x8 kf = *(const bf16x8*)(sK + (kt * 32 + l32) * KROW + s * 32 + h * 16);
;           S[kt] = MFMA32(kf, qf[s], s == 0 ? cinit : S[kt]);
;         }
;       }
;       if (tile < 64 && maskmode == 1) {
;         int qr = tq >> 6, qc = tq & 63;
;         int ws = min(max(qc - 8, 0), 48);
;         int dr = tile - qr + 7;
; #pragma unroll
;         for (int kt = 0; kt < 2; ++kt)
; #pragma unroll
;           for (int r = 0; r < 16; ++r) {
;             int kc = kt * 32 + crow(r, h);
;             bool ok = (unsigned)(kc - ws) < 16u;
;             int bi = ok ? (dr * 31 + kc - qc + 15) : 0;
;             float bv = s_rpb[bi];
;             S[kt][r] = ok ? (S[kt][r] + bv) : -INFINITY;
;           }
;       } else if (tile < 64 && maskmode == 2) {
; #pragma unroll
;         for (int kt = 0; kt < 2; ++kt)
; #pragma unroll
;           for (int r = 0; r < 16; ++r) {
;             int tk = tile * 64 + kt * 32 + crow(r, h);
;             int dd = tq - tk;
;             bool ok = (dd <= 128) && (dd >= -128);
;             S[kt][r] = ok ? S[kt][r] : -INFINITY;
;           }
;       }
; #pragma unroll
;       for (int r = 0; r < 16; ++r) {
;         S[0][r] = __builtin_amdgcn_exp2f(S[0][r]);
;         S[1][r] = __builtin_amdgcn_exp2f(S[1][r]);
;       }
; #pragma unroll
;       for (int kt = 0; kt < 2; ++kt)
; #pragma unroll
;         for (int s2 = 0; s2 < 2; ++s2) {
;           uint4 pw;
;           pw.x = pack_bf16(S[kt][8 * s2 + 0], S[kt][8 * s2 + 1]);
;           pw.y = pack_bf16(S[kt][8 * s2 + 2], S[kt][8 * s2 + 3]);
;           pw.z = pack_bf16(S[kt][8 * s2 + 4], S[kt][8 * s2 + 5]);
;           pw.w = pack_bf16(S[kt][8 * s2 + 6], S[kt][8 * s2 + 7]);
;           bf16x8 pf = __builtin_bit_cast(bf16x8, pw);
;           const int koff = (kt * 32 + 16 * s2 + 8 * h) * 2;
;           {
;             bf16x8 vf = *(const bf16x8*)(sV + l32 * VROW + koff);
;             o0 = MFMA32(vf, pf, o0);
;             lacc = MFMA32(ones, pf, lacc);
;           }
;           {
;             bf16x8 vf = *(const bf16x8*)(sV + (32 + l32) * VROW + koff);
;             o1 = MFMA32(vf, pf, o1);
;           }
;         }
.Lattn0_noprio:
	s_branch .LBB0_261
.LBB0_260:
	ds_read_b128 v[82:85], v144 offset:18432
	ds_read_b128 v[86:89], v144 offset:18464
	s_mov_b64 s[6:7], 0x100
	s_add_i32 s2, s2, 2
	v_lshl_add_u64 v[138:139], v[138:139], 0, s[6:7]
	s_waitcnt lgkmcnt(1)
	v_mfma_f32_32x32x16_bf16 v[66:81], v[82:85], v[98:101], v[2:17]
	ds_read_b128 v[82:85], v144 offset:18496
	ds_read_b128 v[130:133], v144 offset:23040
	v_lshl_add_u64 v[136:137], v[136:137], 0, s[96:97]
	s_andn2_b64 vcc, exec, s[0:1]
	s_waitcnt lgkmcnt(2)
	v_mfma_f32_32x32x16_bf16 v[66:81], v[86:89], v[102:105], v[66:81]
	s_waitcnt lgkmcnt(1)
	v_mfma_f32_32x32x16_bf16 v[66:81], v[82:85], v[106:109], v[66:81]
	ds_read_b128 v[82:85], v144 offset:18528
	s_waitcnt lgkmcnt(0)
	v_mfma_f32_32x32x16_bf16 v[66:81], v[82:85], v[110:113], v[66:81]
	v_mfma_f32_32x32x16_bf16 v[82:97], v[130:133], v[98:101], v[2:17]
	ds_read_b128 v[130:133], v144 offset:23072
	s_nop 9
	v_exp_f32_e32 v66, v66
	v_exp_f32_e32 v67, v67
	v_exp_f32_e32 v68, v68
	v_exp_f32_e32 v69, v69
	v_exp_f32_e32 v70, v70
	v_exp_f32_e32 v71, v71
	s_waitcnt lgkmcnt(0)
	v_mfma_f32_32x32x16_bf16 v[82:97], v[130:133], v[102:105], v[82:97]
	ds_read_b128 v[130:133], v144 offset:23104
	v_exp_f32_e32 v72, v72
	v_exp_f32_e32 v73, v73
	v_add_f32_e32 v51, v51, v66
	v_add_f32_e32 v52, v52, v67
	v_add_f32_e32 v51, v51, v68
	v_add_f32_e32 v52, v52, v69
	v_cvt_pk_bf16_f32 v66, v66, v67
	v_cvt_pk_bf16_f32 v67, v68, v69
	s_waitcnt lgkmcnt(0)
	v_mfma_f32_32x32x16_bf16 v[82:97], v[130:133], v[106:109], v[82:97]
	ds_read_b128 v[130:133], v144 offset:23136
	v_add_f32_e32 v51, v51, v70
	v_add_f32_e32 v52, v52, v71
	v_cvt_pk_bf16_f32 v68, v70, v71
	v_add_f32_e32 v51, v51, v72
	v_add_f32_e32 v52, v52, v73
	v_cvt_pk_bf16_f32 v69, v72, v73
	v_exp_f32_e32 v145, v78
	v_exp_f32_e32 v146, v79
	s_waitcnt lgkmcnt(0)
	v_mfma_f32_32x32x16_bf16 v[82:97], v[130:133], v[110:113], v[82:97]
	v_exp_f32_e32 v147, v80
	v_exp_f32_e32 v148, v81
	v_exp_f32_e32 v130, v74
	v_exp_f32_e32 v131, v75
	v_exp_f32_e32 v132, v76
	v_exp_f32_e32 v133, v77
	ds_read_b128 v[70:73], v142 offset:27648
	ds_read_b128 v[74:77], v142 offset:27680
	ds_read_b128 v[78:81], v142 offset:32256
	v_add_f32_e32 v51, v51, v145
	v_add_f32_e32 v52, v52, v146
	v_add_f32_e32 v51, v51, v147
	v_add_f32_e32 v52, v52, v148
	v_exp_f32_e32 v82, v82
	s_waitcnt lgkmcnt(2)
	v_mfma_f32_32x32x16_bf16 v[34:49], v[70:73], v[66:69], v[34:49]
	v_exp_f32_e32 v83, v83
	v_exp_f32_e32 v84, v84
	v_exp_f32_e32 v85, v85
	v_add_f32_e32 v51, v51, v130
	v_add_f32_e32 v52, v52, v131
	v_add_f32_e32 v51, v51, v132
	v_add_f32_e32 v52, v52, v133
	v_exp_f32_e32 v86, v86
	v_exp_f32_e32 v87, v87
	v_exp_f32_e32 v88, v88
	v_exp_f32_e32 v89, v89
	s_waitcnt lgkmcnt(0)
	v_mfma_f32_32x32x16_bf16 v[18:33], v[78:81], v[66:69], v[18:33]
	v_cvt_pk_bf16_f32 v66, v130, v131
	v_cvt_pk_bf16_f32 v67, v132, v133
	v_cvt_pk_bf16_f32 v68, v145, v146
	v_cvt_pk_bf16_f32 v69, v147, v148
	v_exp_f32_e32 v90, v90
	v_exp_f32_e32 v91, v91
	v_exp_f32_e32 v92, v92
	v_mfma_f32_32x32x16_bf16 v[34:49], v[74:77], v[66:69], v[34:49]
	ds_read_b128 v[74:77], v142 offset:32288
	v_exp_f32_e32 v93, v93
	v_exp_f32_e32 v94, v94
	v_exp_f32_e32 v95, v95
	v_exp_f32_e32 v96, v96
	v_exp_f32_e32 v97, v97
	v_add_f32_e32 v51, v51, v82
	v_add_f32_e32 v52, v52, v83
	s_waitcnt lgkmcnt(0)
	v_mfma_f32_32x32x16_bf16 v[18:33], v[74:77], v[66:69], v[18:33]
	ds_read_b128 v[74:77], v142 offset:27712
	v_add_f32_e32 v51, v51, v84
	v_add_f32_e32 v52, v52, v85
	v_add_f32_e32 v51, v51, v86
	v_add_f32_e32 v52, v52, v87
	v_cvt_pk_bf16_f32 v66, v82, v83
	v_cvt_pk_bf16_f32 v67, v84, v85
	v_cvt_pk_bf16_f32 v68, v86, v87
	v_cvt_pk_bf16_f32 v69, v88, v89
	s_waitcnt lgkmcnt(0)
	s_nop 0
	v_mfma_f32_32x32x16_bf16 v[34:49], v[74:77], v[66:69], v[34:49]
	ds_read_b128 v[74:77], v142 offset:32320
	v_add_f32_e32 v51, v51, v88
	v_add_f32_e32 v52, v52, v89
	v_add_f32_e32 v51, v51, v90
	v_add_f32_e32 v52, v52, v91
	s_waitcnt lgkmcnt(0)
	v_mfma_f32_32x32x16_bf16 v[18:33], v[74:77], v[66:69], v[18:33]
	v_cvt_pk_bf16_f32 v66, v90, v91
	v_cvt_pk_bf16_f32 v67, v92, v93
	v_cvt_pk_bf16_f32 v68, v94, v95
	v_cvt_pk_bf16_f32 v69, v96, v97
	ds_read_b128 v[74:77], v142 offset:27744
	ds_read_b128 v[70:73], v142 offset:32352
	v_add_f32_e32 v51, v51, v92
	v_add_f32_e32 v52, v52, v93
	v_add_f32_e32 v51, v51, v94
	v_add_f32_e32 v52, v52, v95
	v_add_f32_e32 v51, v51, v96
	v_add_f32_e32 v52, v52, v97
	s_waitcnt lgkmcnt(0)
	s_barrier
	v_mfma_f32_32x32x16_bf16 v[34:49], v[74:77], v[66:69], v[34:49]
	v_mfma_f32_32x32x16_bf16 v[18:33], v[70:73], v[66:69], v[18:33]
	s_cbranch_vccz .LBB0_267

; DI void attn_item(const Params& p, int layer, int item, char* smem) {
;     ...
;   float l_tot = lacc[0];
;   if (hasSink) l_tot += __builtin_amdgcn_exp2f(sinkv * LOG2E - m_fix);
;   float inv = 1.f / l_tot;
;   int T = (mode == 3) ? (TLAT + b * 256 + (qpos - 4096)) : (b * 4096 + qpos);
;   u16* od = p.O + (size_t)T * LDK + head16 * 64;
; #pragma unroll
;   for (int g = 0; g < 4; ++g) {
;     int d0 = 8 * g + 4 * h;
;     *(uint2*)(od + d0) = make_uint2(pack_bf16(o0[4 * g] * inv, o0[4 * g + 1] * inv), pack_bf16(o0[4 * g + 2] * inv, o0[4 * g + 3] * inv));
;     *(uint2*)(od + 32 + d0) = make_uint2(pack_bf16(o1[4 * g] * inv, o1[4 * g + 1] * inv), pack_bf16(o1[4 * g + 2] * inv, o1[4 * g + 3] * inv));
;   }
.LBB0_267:
	s_setprio 0
	s_nop 5
	v_add_f32_e32 v51, v51, v52
	s_nop 0
	v_mov_b32_e32 v52, v51
	s_nop 1
	v_permlane32_swap_b32_e32 v51, v52
	s_nop 1
	v_add_f32_e32 v50, v50, v51
	v_add_f32_e32 v50, v50, v52
	v_div_scale_f32 v0, s[0:1], v50, v50, 1.0
	v_rcp_f32_e32 v3, v0
	v_lshl_add_u32 v2, s5, 12, v134
	s_lshl_b32 s0, s4, 6
	s_ashr_i32 s1, s0, 31
	v_fma_f32 v4, -v0, v3, 1.0
	v_fmac_f32_e32 v3, v4, v3
	v_div_scale_f32 v4, vcc, 1.0, v50, 1.0
	v_mul_f32_e32 v5, v4, v3
	v_fma_f32 v6, -v0, v5, v4
	v_fmac_f32_e32 v5, v6, v3
	v_fma_f32 v0, -v0, v5, v4
	v_div_fmas_f32 v0, v0, v3, v5
	v_ashrrev_i32_e32 v3, 31, v2
	v_lshlrev_b64 v[2:3], 11, v[2:3]
	v_div_fixup_f32 v4, v0, v50, 1.0
	v_lshl_add_u64 v[2:3], s[90:91], 0, v[2:3]
	v_lshl_add_u64 v[2:3], s[0:1], 1, v[2:3]
	v_pk_mul_f32 v[6:7], v[34:35], v[4:5] op_sel_hi:[1,0]
	v_pk_mul_f32 v[8:9], v[36:37], v[4:5] op_sel_hi:[1,0]
	v_lshlrev_b32_e32 v0, 3, v140
	v_cvt_pk_bf16_f32 v6, v6, v7
	v_cvt_pk_bf16_f32 v7, v8, v9
	v_lshl_add_u64 v[2:3], v[2:3], 0, v[0:1]
	global_store_dwordx2 v[2:3], v[6:7], off offset:1280
	v_pk_mul_f32 v[6:7], v[4:5], v[18:19] op_sel_hi:[0,1]
	v_pk_mul_f32 v[8:9], v[4:5], v[20:21] op_sel_hi:[0,1]
	v_cvt_pk_bf16_f32 v6, v6, v7
	v_cvt_pk_bf16_f32 v7, v8, v9
	global_store_dwordx2 v[2:3], v[6:7], off offset:1344
	v_pk_mul_f32 v[6:7], v[38:39], v[4:5] op_sel_hi:[1,0]
	v_pk_mul_f32 v[8:9], v[40:41], v[4:5] op_sel_hi:[1,0]
	v_cvt_pk_bf16_f32 v6, v6, v7
	v_cvt_pk_bf16_f32 v7, v8, v9
	global_store_dwordx2 v[2:3], v[6:7], off offset:1296
	v_pk_mul_f32 v[6:7], v[4:5], v[22:23] op_sel_hi:[0,1]
	v_pk_mul_f32 v[8:9], v[4:5], v[24:25] op_sel_hi:[0,1]
	v_cvt_pk_bf16_f32 v6, v6, v7
	v_cvt_pk_bf16_f32 v7, v8, v9
	global_store_dwordx2 v[2:3], v[6:7], off offset:1360
	v_pk_mul_f32 v[6:7], v[42:43], v[4:5] op_sel_hi:[1,0]
	v_pk_mul_f32 v[8:9], v[44:45], v[4:5] op_sel_hi:[1,0]
	v_cvt_pk_bf16_f32 v6, v6, v7
	v_cvt_pk_bf16_f32 v7, v8, v9
	global_store_dwordx2 v[2:3], v[6:7], off offset:1312
	v_pk_mul_f32 v[6:7], v[4:5], v[26:27] op_sel_hi:[0,1]
	v_pk_mul_f32 v[8:9], v[4:5], v[28:29] op_sel_hi:[0,1]
	v_cvt_pk_bf16_f32 v6, v6, v7
	v_cvt_pk_bf16_f32 v7, v8, v9
	global_store_dwordx2 v[2:3], v[6:7], off offset:1376
	v_pk_mul_f32 v[6:7], v[46:47], v[4:5] op_sel_hi:[1,0]
	v_pk_mul_f32 v[8:9], v[48:49], v[4:5] op_sel_hi:[1,0]
	v_cvt_pk_bf16_f32 v6, v6, v7
	v_cvt_pk_bf16_f32 v7, v8, v9
	global_store_dwordx2 v[2:3], v[6:7], off offset:1328
	v_pk_mul_f32 v[6:7], v[4:5], v[30:31] op_sel_hi:[0,1]
	v_pk_mul_f32 v[4:5], v[4:5], v[32:33] op_sel_hi:[0,1]
	v_cvt_pk_bf16_f32 v6, v6, v7
	v_cvt_pk_bf16_f32 v7, v4, v5
	global_store_dwordx2 v[2:3], v[6:7], off offset:1392
	s_and_saveexec_b64 s[0:1], s[68:69]
	s_cbranch_execz .LBB0_236
	s_branch .LBB0_498
